# v75 + GEMM accumulator re-zeroing with 64-bit moves + in-proj epilogue waits for outstanding loads only on gate tiles
# baseline (speedup 1.0000x reference)
; #define PG8_LDA(dst, b, h) do { _Pragma("unroll") for (int m = 0; m < 4; ++m) _Pragma("unroll") for (int k = 0; k < 2; ++k) dst[m][k] = *(const PG8_LAS bf16x8*)(lds + PG8_SA(b, h) + aoff + m * 2048 + k * 1024); } while (0)
; template <class Prob, class Epi, class Sched>
; __device__ __forceinline__ void gemm_phase(PG8_LAS unsigned char* lds, const Prob g, const Sched& S, const Epi& E) {
;     ...
;         const bool has_next = S.next(ui + 1, nxt);
;         const char* nA = has_next ? g.abase(nxt) : cA; const char* nB = has_next ? g.bbase(nxt) : cB;
;         for (int t = 0; t < nt; t += 2) {
;             const bool last = (t == nt - 2);
;             const char* a1 = cA + (size_t)(t + 1) * kstep;
;             const char* a2 = last ? nA : cA + (size_t)(t + 2) * kstep; const char* b2 = last ? nB : cB + (size_t)(t + 2) * kstep;
;             const char* a3 = a2 + kstep; const char* b3 = b2 + kstep;
;             PG8_LDB(B0, 0, 0); PG8_LDB(B1, 0, 1); PG8_SCHED; PG8_LDA(At, 0, 0); PG8_STAGE(PG8_SA(1, 1), a1 + hstepA, voffA);
;             PG8_WAIT_V(8); PG8_WAIT_L(0); PG8_BAR; PG8_MMA(0, 0, At, B0); PG8_MMA(0, 1, At, B1); PG8_BAR; PG8_SCHED;
;             PG8_LDA(At, 0, 1); PG8_STAGE(PG8_SB(0, 0), b2, voffB); PG8_STAGE(PG8_SB(0, 1), b2 + hstepB, voffB); PG8_STAGE(PG8_SA(0, 0), a2, voffA);
;             PG8_WAIT_V(8); PG8_WAIT_L(0); PG8_BAR; PG8_MMA(1, 0, At, B0); PG8_MMA(1, 1, At, B1); PG8_BAR; PG8_SCHED;
;             PG8_LDB(B0, 1, 0); PG8_LDB(B1, 1, 1); PG8_SCHED; PG8_LDA(At, 1, 0); PG8_STAGE(PG8_SA(0, 1), a2 + hstepA, voffA);
;             PG8_WAIT_V(8); PG8_WAIT_L(0); PG8_BAR; PG8_MMA(0, 0, At, B0); PG8_MMA(0, 1, At, B1); PG8_BAR; PG8_SCHED;
;             PG8_LDA(At, 1, 1); PG8_STAGE(PG8_SB(1, 0), b3, voffB); PG8_STAGE(PG8_SB(1, 1), b3 + hstepB, voffB); PG8_STAGE(PG8_SA(1, 0), a3, voffA);
;             PG8_WAIT_V(8); PG8_WAIT_L(0); PG8_BAR; PG8_MMA(1, 0, At, B0); PG8_MMA(1, 1, At, B1); PG8_BAR; PG8_SCHED;
;         }
;         if (wr == 0) PG8_BAR;
;         E(acc, cur, wr, wc, fr, fq);
;         if (!has_next) break;
; #pragma unroll
;         for (int a = 0; a < 2; ++a)
; #pragma unroll
;             for (int b = 0; b < 2; ++b)
; #pragma unroll
;                 for (int m = 0; m < 4; ++m)
; #pragma unroll
;                     for (int n = 0; n < 2; ++n) acc[a][b][m][n] = (f32x4){0.f, 0.f, 0.f, 0.f};
;         cur = nxt; cA = nA; cB = nB; ++ui;
.LBB0_270:
	s_ashr_i32 s27, s26, 31
	s_lshl_b64 s[28:29], s[26:27], 20
	s_add_u32 s28, s10, s28
	s_addc_u32 s29, s11, s29
	s_and_b64 s[30:31], s[6:7], exec
	s_cselect_b32 s27, s29, s9
	s_cselect_b32 s38, s28, s8
	s_ashr_i32 s25, s24, 31
	s_lshl_b64 s[30:31], s[24:25], 20
	s_add_u32 s30, s12, s30
	s_addc_u32 s31, s13, s31
	s_and_b64 s[36:37], s[6:7], exec
	s_cselect_b32 s25, s31, s35
	s_cselect_b32 s39, s30, s34
	s_add_u32 s8, s8, 0x80080
	s_addc_u32 s9, s9, 0
	s_add_u32 s44, s34, 0x100
	v_mov_b32_e32 v2, 0
	s_addc_u32 s45, s35, 0
	s_mov_b32 s66, -2
	v_mov_b32_e32 v3, v2
	v_mov_b64_e32 v[4:5], v[2:3]
	v_mov_b64_e32 v[6:7], v[2:3]
	v_mov_b64_e32 v[8:9], v[2:3]
	v_mov_b64_e32 v[18:19], v[2:3]
	v_mov_b64_e32 v[20:21], v[2:3]
	v_mov_b64_e32 v[22:23], v[2:3]
	v_mov_b64_e32 v[24:25], v[2:3]
	v_mov_b64_e32 v[34:35], v[2:3]
	v_mov_b64_e32 v[36:37], v[2:3]
	v_mov_b64_e32 v[38:39], v[2:3]
	v_mov_b64_e32 v[40:41], v[2:3]
	v_mov_b64_e32 v[50:51], v[2:3]
	v_mov_b64_e32 v[52:53], v[2:3]
	v_mov_b64_e32 v[54:55], v[2:3]
	v_mov_b64_e32 v[56:57], v[2:3]
	v_mov_b64_e32 v[10:11], v[2:3]
	v_mov_b64_e32 v[12:13], v[2:3]
	v_mov_b64_e32 v[14:15], v[2:3]
	v_mov_b64_e32 v[16:17], v[2:3]
	v_mov_b64_e32 v[26:27], v[2:3]
	v_mov_b64_e32 v[28:29], v[2:3]
	v_mov_b64_e32 v[30:31], v[2:3]
	v_mov_b64_e32 v[32:33], v[2:3]
	v_mov_b64_e32 v[42:43], v[2:3]
	v_mov_b64_e32 v[44:45], v[2:3]
	v_mov_b64_e32 v[46:47], v[2:3]
	v_mov_b64_e32 v[48:49], v[2:3]
	v_mov_b64_e32 v[58:59], v[2:3]
	v_mov_b64_e32 v[60:61], v[2:3]
	v_mov_b64_e32 v[62:63], v[2:3]
	v_mov_b64_e32 v[64:65], v[2:3]
	v_mov_b64_e32 v[82:83], v[2:3]
	v_mov_b64_e32 v[84:85], v[2:3]
	v_mov_b64_e32 v[86:87], v[2:3]
	v_mov_b64_e32 v[88:89], v[2:3]
	v_mov_b64_e32 v[98:99], v[2:3]
	v_mov_b64_e32 v[100:101], v[2:3]
	v_mov_b64_e32 v[102:103], v[2:3]
	v_mov_b64_e32 v[104:105], v[2:3]
	v_mov_b64_e32 v[114:115], v[2:3]
	v_mov_b64_e32 v[116:117], v[2:3]
	v_mov_b64_e32 v[118:119], v[2:3]
	v_mov_b64_e32 v[120:121], v[2:3]
	v_mov_b64_e32 v[130:131], v[2:3]
	v_mov_b64_e32 v[132:133], v[2:3]
	v_mov_b64_e32 v[134:135], v[2:3]
	v_mov_b64_e32 v[136:137], v[2:3]
	v_mov_b64_e32 v[90:91], v[2:3]
	v_mov_b64_e32 v[92:93], v[2:3]
	v_mov_b64_e32 v[94:95], v[2:3]
	v_mov_b64_e32 v[96:97], v[2:3]
	v_mov_b64_e32 v[106:107], v[2:3]
	v_mov_b64_e32 v[108:109], v[2:3]
	v_mov_b64_e32 v[110:111], v[2:3]
	v_mov_b64_e32 v[112:113], v[2:3]
	v_mov_b64_e32 v[122:123], v[2:3]
	v_mov_b64_e32 v[124:125], v[2:3]
	v_mov_b64_e32 v[126:127], v[2:3]
	v_mov_b64_e32 v[128:129], v[2:3]
	v_mov_b64_e32 v[138:139], v[2:3]
	v_mov_b64_e32 v[140:141], v[2:3]
	v_mov_b64_e32 v[142:143], v[2:3]
	v_mov_b64_e32 v[144:145], v[2:3]

;     __device__ __forceinline__ void operator()(const f32x4 (&acc)[2][2][4][2], const Unit& u, int wr, int wc, int fr, int fq) const {
;     ...
;         const int colt = isg ? (u.pn - 24) * BM : u.pn * BM; bf16_t* base = isg ? gate : qkv; const int ldc = isg ? 4096 : 6144;
;         const int col0 = colt + wc * 32 + 8 * fq;
;         f32x4 bv[2][2];
; #pragma unroll
;         for (int bj = 0; bj < 2; ++bj)
; #pragma unroll
;             for (int n = 0; n < 2; ++n) bv[bj][n] = isg ? *(const f32x4*)(bgate + col0 + bj * HALF + 4 * n) : (f32x4){0.f, 0.f, 0.f, 0.f};
; #pragma unroll
;         for (int ai = 0; ai < 2; ++ai)
; #pragma unroll
;             for (int m = 0; m < 4; ++m) { bf16_t* rowp = base + (size_t)(row0 + ai * HALF + m * 16) * ldc + col0;
; #pragma unroll
;                 for (int bj = 0; bj < 2; ++bj) { f32x4 v0 = acc[ai][bj][m][0] + bv[bj][0], v1 = acc[ai][bj][m][1] + bv[bj][1];
.LBB0_280:
	s_mov_b64 s[34:35], 0x1800
	s_and_b64 vcc, exec, s[8:9]
	v_mov_b32_e32 v67, 0
	v_mov_b32_e32 v68, 0
	v_mov_b32_e32 v69, 0
	s_cbranch_vccnz .LBB0_282
	global_load_dwordx4 v[66:69], v[158:159], off offset:528
	s_waitcnt vmcnt(0)
	s_mov_b64 s[34:35], 0x1000
.LBB0_282:
	v_cndmask_b32_e64 v1, 0, 1, s[38:39]
	v_pk_add_f32 v[144:145], v[144:145], v[80:81]
	v_pk_add_f32 v[142:143], v[142:143], v[78:79]
	v_pk_add_f32 v[158:159], v[140:141], v[76:77]
	v_pk_add_f32 v[160:161], v[138:139], v[74:75]
	v_cmp_ne_u32_e64 s[8:9], 1, v1
	s_andn2_b64 vcc, exec, s[38:39]
	s_mov_b64 s[38:39], -1
	s_cbranch_vccnz .LBB0_284
	s_mov_b64 s[38:39], 0

; #define PG8_LDA(dst, b, h) do { _Pragma("unroll") for (int m = 0; m < 4; ++m) _Pragma("unroll") for (int k = 0; k < 2; ++k) dst[m][k] = *(const PG8_LAS bf16x8*)(lds + PG8_SA(b, h) + aoff + m * 2048 + k * 1024); } while (0)
; template <class Prob, class Epi, class Sched>
; __device__ __forceinline__ void gemm_phase(PG8_LAS unsigned char* lds, const Prob g, const Sched& S, const Epi& E) {
;     ...
;         const bool has_next = S.next(ui + 1, nxt);
;         const char* nA = has_next ? g.abase(nxt) : cA; const char* nB = has_next ? g.bbase(nxt) : cB;
;         for (int t = 0; t < nt; t += 2) {
;             const bool last = (t == nt - 2);
;             const char* a1 = cA + (size_t)(t + 1) * kstep;
;             const char* a2 = last ? nA : cA + (size_t)(t + 2) * kstep; const char* b2 = last ? nB : cB + (size_t)(t + 2) * kstep;
;             const char* a3 = a2 + kstep; const char* b3 = b2 + kstep;
;             PG8_LDB(B0, 0, 0); PG8_LDB(B1, 0, 1); PG8_SCHED; PG8_LDA(At, 0, 0); PG8_STAGE(PG8_SA(1, 1), a1 + hstepA, voffA);
;             PG8_WAIT_V(8); PG8_WAIT_L(0); PG8_BAR; PG8_MMA(0, 0, At, B0); PG8_MMA(0, 1, At, B1); PG8_BAR; PG8_SCHED;
;             PG8_LDA(At, 0, 1); PG8_STAGE(PG8_SB(0, 0), b2, voffB); PG8_STAGE(PG8_SB(0, 1), b2 + hstepB, voffB); PG8_STAGE(PG8_SA(0, 0), a2, voffA);
;             PG8_WAIT_V(8); PG8_WAIT_L(0); PG8_BAR; PG8_MMA(1, 0, At, B0); PG8_MMA(1, 1, At, B1); PG8_BAR; PG8_SCHED;
;             PG8_LDB(B0, 1, 0); PG8_LDB(B1, 1, 1); PG8_SCHED; PG8_LDA(At, 1, 0); PG8_STAGE(PG8_SA(0, 1), a2 + hstepA, voffA);
;             PG8_WAIT_V(8); PG8_WAIT_L(0); PG8_BAR; PG8_MMA(0, 0, At, B0); PG8_MMA(0, 1, At, B1); PG8_BAR; PG8_SCHED;
;             PG8_LDA(At, 1, 1); PG8_STAGE(PG8_SB(1, 0), b3, voffB); PG8_STAGE(PG8_SB(1, 1), b3 + hstepB, voffB); PG8_STAGE(PG8_SA(1, 0), a3, voffA);
;             PG8_WAIT_V(8); PG8_WAIT_L(0); PG8_BAR; PG8_MMA(1, 0, At, B0); PG8_MMA(1, 1, At, B1); PG8_BAR; PG8_SCHED;
;         }
;         if (wr == 0) PG8_BAR;
;         E(acc, cur, wr, wc, fr, fq);
;         if (!has_next) break;
; #pragma unroll
;         for (int a = 0; a < 2; ++a)
; #pragma unroll
;             for (int b = 0; b < 2; ++b)
; #pragma unroll
;                 for (int m = 0; m < 4; ++m)
; #pragma unroll
;                     for (int n = 0; n < 2; ++n) acc[a][b][m][n] = (f32x4){0.f, 0.f, 0.f, 0.f};
;         cur = nxt; cA = nA; cB = nB; ++ui;
.LBB0_364:
	s_ashr_i32 s37, s36, 31
	s_lshl_b64 s[16:17], s[36:37], 20
	s_add_u32 s68, s38, s16
	s_addc_u32 s69, s39, s17
	s_and_b64 s[8:9], s[8:9], exec
	s_cselect_b32 s16, s69, s13
	s_cselect_b32 s17, s68, s12
	s_add_u32 s8, s12, 0x80080
	s_addc_u32 s9, s13, 0
	s_add_u32 s18, s10, 0x100
	v_mov_b32_e32 v2, 0
	s_addc_u32 s19, s11, 0
	s_mov_b32 s20, -2
	v_mov_b32_e32 v3, v2
	v_mov_b64_e32 v[4:5], v[2:3]
	v_mov_b64_e32 v[6:7], v[2:3]
	v_mov_b64_e32 v[8:9], v[2:3]
	v_mov_b64_e32 v[10:11], v[2:3]
	v_mov_b64_e32 v[12:13], v[2:3]
	v_mov_b64_e32 v[14:15], v[2:3]
	v_mov_b64_e32 v[16:17], v[2:3]
	v_mov_b64_e32 v[18:19], v[2:3]
	v_mov_b64_e32 v[20:21], v[2:3]
	v_mov_b64_e32 v[22:23], v[2:3]
	v_mov_b64_e32 v[24:25], v[2:3]
	v_mov_b64_e32 v[26:27], v[2:3]
	v_mov_b64_e32 v[28:29], v[2:3]
	v_mov_b64_e32 v[30:31], v[2:3]
	v_mov_b64_e32 v[32:33], v[2:3]
	v_mov_b64_e32 v[66:67], v[2:3]
	v_mov_b64_e32 v[68:69], v[2:3]
	v_mov_b64_e32 v[70:71], v[2:3]
	v_mov_b64_e32 v[72:73], v[2:3]
	v_mov_b64_e32 v[74:75], v[2:3]
	v_mov_b64_e32 v[76:77], v[2:3]
	v_mov_b64_e32 v[78:79], v[2:3]
	v_mov_b64_e32 v[80:81], v[2:3]
	v_mov_b64_e32 v[82:83], v[2:3]
	v_mov_b64_e32 v[84:85], v[2:3]
	v_mov_b64_e32 v[86:87], v[2:3]
	v_mov_b64_e32 v[88:89], v[2:3]
	v_mov_b64_e32 v[90:91], v[2:3]
	v_mov_b64_e32 v[92:93], v[2:3]
	v_mov_b64_e32 v[94:95], v[2:3]
	v_mov_b64_e32 v[96:97], v[2:3]
	v_mov_b64_e32 v[34:35], v[2:3]
	v_mov_b64_e32 v[36:37], v[2:3]
	v_mov_b64_e32 v[38:39], v[2:3]
	v_mov_b64_e32 v[40:41], v[2:3]
	v_mov_b64_e32 v[42:43], v[2:3]
	v_mov_b64_e32 v[44:45], v[2:3]
	v_mov_b64_e32 v[46:47], v[2:3]
	v_mov_b64_e32 v[48:49], v[2:3]
	v_mov_b64_e32 v[50:51], v[2:3]
	v_mov_b64_e32 v[52:53], v[2:3]
	v_mov_b64_e32 v[54:55], v[2:3]
	v_mov_b64_e32 v[56:57], v[2:3]
	v_mov_b64_e32 v[58:59], v[2:3]
	v_mov_b64_e32 v[60:61], v[2:3]
	v_mov_b64_e32 v[62:63], v[2:3]
	v_mov_b64_e32 v[64:65], v[2:3]
	v_mov_b64_e32 v[98:99], v[2:3]
	v_mov_b64_e32 v[100:101], v[2:3]
	v_mov_b64_e32 v[102:103], v[2:3]
	v_mov_b64_e32 v[104:105], v[2:3]
	v_mov_b64_e32 v[106:107], v[2:3]
	v_mov_b64_e32 v[108:109], v[2:3]
	v_mov_b64_e32 v[110:111], v[2:3]
	v_mov_b64_e32 v[112:113], v[2:3]
	v_mov_b64_e32 v[114:115], v[2:3]
	v_mov_b64_e32 v[116:117], v[2:3]
	v_mov_b64_e32 v[118:119], v[2:3]
	v_mov_b64_e32 v[120:121], v[2:3]
	v_mov_b64_e32 v[122:123], v[2:3]
	v_mov_b64_e32 v[124:125], v[2:3]
	v_mov_b64_e32 v[126:127], v[2:3]
	v_mov_b64_e32 v[128:129], v[2:3]

; #define PG8_LDA(dst, b, h) do { _Pragma("unroll") for (int m = 0; m < 4; ++m) _Pragma("unroll") for (int k = 0; k < 2; ++k) dst[m][k] = *(const PG8_LAS bf16x8*)(lds + PG8_SA(b, h) + aoff + m * 2048 + k * 1024); } while (0)
; template <class Prob, class Epi, class Sched>
; __device__ __forceinline__ void gemm_phase(PG8_LAS unsigned char* lds, const Prob g, const Sched& S, const Epi& E) {
;     ...
;         const bool has_next = S.next(ui + 1, nxt);
;         const char* nA = has_next ? g.abase(nxt) : cA; const char* nB = has_next ? g.bbase(nxt) : cB;
;         for (int t = 0; t < nt; t += 2) {
;             const bool last = (t == nt - 2);
;             const char* a1 = cA + (size_t)(t + 1) * kstep;
;             const char* a2 = last ? nA : cA + (size_t)(t + 2) * kstep; const char* b2 = last ? nB : cB + (size_t)(t + 2) * kstep;
;             const char* a3 = a2 + kstep; const char* b3 = b2 + kstep;
;             PG8_LDB(B0, 0, 0); PG8_LDB(B1, 0, 1); PG8_SCHED; PG8_LDA(At, 0, 0); PG8_STAGE(PG8_SA(1, 1), a1 + hstepA, voffA);
;             PG8_WAIT_V(8); PG8_WAIT_L(0); PG8_BAR; PG8_MMA(0, 0, At, B0); PG8_MMA(0, 1, At, B1); PG8_BAR; PG8_SCHED;
;             PG8_LDA(At, 0, 1); PG8_STAGE(PG8_SB(0, 0), b2, voffB); PG8_STAGE(PG8_SB(0, 1), b2 + hstepB, voffB); PG8_STAGE(PG8_SA(0, 0), a2, voffA);
;             PG8_WAIT_V(8); PG8_WAIT_L(0); PG8_BAR; PG8_MMA(1, 0, At, B0); PG8_MMA(1, 1, At, B1); PG8_BAR; PG8_SCHED;
;             PG8_LDB(B0, 1, 0); PG8_LDB(B1, 1, 1); PG8_SCHED; PG8_LDA(At, 1, 0); PG8_STAGE(PG8_SA(0, 1), a2 + hstepA, voffA);
;             PG8_WAIT_V(8); PG8_WAIT_L(0); PG8_BAR; PG8_MMA(0, 0, At, B0); PG8_MMA(0, 1, At, B1); PG8_BAR; PG8_SCHED;
;             PG8_LDA(At, 1, 1); PG8_STAGE(PG8_SB(1, 0), b3, voffB); PG8_STAGE(PG8_SB(1, 1), b3 + hstepB, voffB); PG8_STAGE(PG8_SA(1, 0), a3, voffA);
;             PG8_WAIT_V(8); PG8_WAIT_L(0); PG8_BAR; PG8_MMA(1, 0, At, B0); PG8_MMA(1, 1, At, B1); PG8_BAR; PG8_SCHED;
;         }
;         if (wr == 0) PG8_BAR;
;         E(acc, cur, wr, wc, fr, fq);
;         if (!has_next) break;
; #pragma unroll
;         for (int a = 0; a < 2; ++a)
; #pragma unroll
;             for (int b = 0; b < 2; ++b)
; #pragma unroll
;                 for (int m = 0; m < 4; ++m)
; #pragma unroll
;                     for (int n = 0; n < 2; ++n) acc[a][b][m][n] = (f32x4){0.f, 0.f, 0.f, 0.f};
;         cur = nxt; cA = nA; cB = nB; ++ui;
.LBB0_607:
	s_ashr_i32 s21, s20, 31
	s_lshl_b64 s[4:5], s[20:21], 17
	s_add_u32 s24, s8, s4
	s_addc_u32 s25, s9, s5
	s_and_b64 s[4:5], s[6:7], exec
	s_cselect_b32 s21, s25, s29
	s_cselect_b32 s70, s24, s28
	s_ashr_i32 s19, s18, 31
	s_lshl_b64 s[4:5], s[18:19], 17
	s_add_u32 s26, s10, s4
	s_addc_u32 s27, s11, s5
	s_and_b64 s[4:5], s[6:7], exec
	v_mov_b32_e32 v2, 0
	s_cselect_b32 s19, s27, s23
	s_cselect_b32 s44, s26, s22
	s_mov_b32 s36, 0
	s_mov_b64 s[30:31], -1
	s_mov_b64 s[34:35], 0
	v_mov_b32_e32 v3, v2
	v_mov_b64_e32 v[4:5], v[2:3]
	v_mov_b64_e32 v[6:7], v[2:3]
	v_mov_b64_e32 v[8:9], v[2:3]
	v_mov_b64_e32 v[10:11], v[2:3]
	v_mov_b64_e32 v[12:13], v[2:3]
	v_mov_b64_e32 v[14:15], v[2:3]
	v_mov_b64_e32 v[16:17], v[2:3]
	v_mov_b64_e32 v[18:19], v[2:3]
	v_mov_b64_e32 v[20:21], v[2:3]
	v_mov_b64_e32 v[22:23], v[2:3]
	v_mov_b64_e32 v[24:25], v[2:3]
	v_mov_b64_e32 v[26:27], v[2:3]
	v_mov_b64_e32 v[28:29], v[2:3]
	v_mov_b64_e32 v[30:31], v[2:3]
	v_mov_b64_e32 v[32:33], v[2:3]
	v_mov_b64_e32 v[46:47], v[2:3]
	v_mov_b64_e32 v[48:49], v[2:3]
	v_mov_b64_e32 v[54:55], v[2:3]
	v_mov_b64_e32 v[56:57], v[2:3]
	v_mov_b64_e32 v[62:63], v[2:3]
	v_mov_b64_e32 v[64:65], v[2:3]
	v_mov_b64_e32 v[70:71], v[2:3]
	v_mov_b64_e32 v[72:73], v[2:3]
	v_mov_b64_e32 v[78:79], v[2:3]
	v_mov_b64_e32 v[80:81], v[2:3]
	v_mov_b64_e32 v[86:87], v[2:3]
	v_mov_b64_e32 v[88:89], v[2:3]
	v_mov_b64_e32 v[90:91], v[2:3]
	v_mov_b64_e32 v[92:93], v[2:3]
	v_mov_b64_e32 v[94:95], v[2:3]
	v_mov_b64_e32 v[96:97], v[2:3]
	v_mov_b64_e32 v[34:35], v[2:3]
	v_mov_b64_e32 v[36:37], v[2:3]
	v_mov_b64_e32 v[38:39], v[2:3]
	v_mov_b64_e32 v[40:41], v[2:3]
	v_mov_b64_e32 v[42:43], v[2:3]
	v_mov_b64_e32 v[44:45], v[2:3]
	v_mov_b64_e32 v[50:51], v[2:3]
	v_mov_b64_e32 v[52:53], v[2:3]
	v_mov_b64_e32 v[58:59], v[2:3]
	v_mov_b64_e32 v[60:61], v[2:3]
	v_mov_b64_e32 v[66:67], v[2:3]
	v_mov_b64_e32 v[68:69], v[2:3]
	v_mov_b64_e32 v[74:75], v[2:3]
	v_mov_b64_e32 v[76:77], v[2:3]
	v_mov_b64_e32 v[82:83], v[2:3]
	v_mov_b64_e32 v[84:85], v[2:3]
	v_mov_b64_e32 v[98:99], v[2:3]
	v_mov_b64_e32 v[100:101], v[2:3]
	v_mov_b64_e32 v[102:103], v[2:3]
	v_mov_b64_e32 v[104:105], v[2:3]
	v_mov_b64_e32 v[106:107], v[2:3]
	v_mov_b64_e32 v[108:109], v[2:3]
	v_mov_b64_e32 v[110:111], v[2:3]
	v_mov_b64_e32 v[112:113], v[2:3]
	v_mov_b64_e32 v[114:115], v[2:3]
	v_mov_b64_e32 v[116:117], v[2:3]
	v_mov_b64_e32 v[118:119], v[2:3]
	v_mov_b64_e32 v[120:121], v[2:3]
	v_mov_b64_e32 v[122:123], v[2:3]
	v_mov_b64_e32 v[124:125], v[2:3]
	v_mov_b64_e32 v[126:127], v[2:3]
	v_mov_b64_e32 v[128:129], v[2:3]

; #define PG8_LDA(dst, b, h) do { _Pragma("unroll") for (int m = 0; m < 4; ++m) _Pragma("unroll") for (int k = 0; k < 2; ++k) dst[m][k] = *(const PG8_LAS bf16x8*)(lds + PG8_SA(b, h) + aoff + m * 2048 + k * 1024); } while (0)
; template <class Prob, class Epi, class Sched>
; __device__ __forceinline__ void gemm_phase(PG8_LAS unsigned char* lds, const Prob g, const Sched& S, const Epi& E) {
;     ...
;         const bool has_next = S.next(ui + 1, nxt);
;         const char* nA = has_next ? g.abase(nxt) : cA; const char* nB = has_next ? g.bbase(nxt) : cB;
;         for (int t = 0; t < nt; t += 2) {
;             const bool last = (t == nt - 2);
;             const char* a1 = cA + (size_t)(t + 1) * kstep;
;             const char* a2 = last ? nA : cA + (size_t)(t + 2) * kstep; const char* b2 = last ? nB : cB + (size_t)(t + 2) * kstep;
;             const char* a3 = a2 + kstep; const char* b3 = b2 + kstep;
;             PG8_LDB(B0, 0, 0); PG8_LDB(B1, 0, 1); PG8_SCHED; PG8_LDA(At, 0, 0); PG8_STAGE(PG8_SA(1, 1), a1 + hstepA, voffA);
;             PG8_WAIT_V(8); PG8_WAIT_L(0); PG8_BAR; PG8_MMA(0, 0, At, B0); PG8_MMA(0, 1, At, B1); PG8_BAR; PG8_SCHED;
;             PG8_LDA(At, 0, 1); PG8_STAGE(PG8_SB(0, 0), b2, voffB); PG8_STAGE(PG8_SB(0, 1), b2 + hstepB, voffB); PG8_STAGE(PG8_SA(0, 0), a2, voffA);
;             PG8_WAIT_V(8); PG8_WAIT_L(0); PG8_BAR; PG8_MMA(1, 0, At, B0); PG8_MMA(1, 1, At, B1); PG8_BAR; PG8_SCHED;
;             PG8_LDB(B0, 1, 0); PG8_LDB(B1, 1, 1); PG8_SCHED; PG8_LDA(At, 1, 0); PG8_STAGE(PG8_SA(0, 1), a2 + hstepA, voffA);
;             PG8_WAIT_V(8); PG8_WAIT_L(0); PG8_BAR; PG8_MMA(0, 0, At, B0); PG8_MMA(0, 1, At, B1); PG8_BAR; PG8_SCHED;
;             PG8_LDA(At, 1, 1); PG8_STAGE(PG8_SB(1, 0), b3, voffB); PG8_STAGE(PG8_SB(1, 1), b3 + hstepB, voffB); PG8_STAGE(PG8_SA(1, 0), a3, voffA);
;             PG8_WAIT_V(8); PG8_WAIT_L(0); PG8_BAR; PG8_MMA(1, 0, At, B0); PG8_MMA(1, 1, At, B1); PG8_BAR; PG8_SCHED;
;         }
;         if (wr == 0) PG8_BAR;
;         E(acc, cur, wr, wc, fr, fq);
;         if (!has_next) break;
; #pragma unroll
;         for (int a = 0; a < 2; ++a)
; #pragma unroll
;             for (int b = 0; b < 2; ++b)
; #pragma unroll
;                 for (int m = 0; m < 4; ++m)
; #pragma unroll
;                     for (int n = 0; n < 2; ++n) acc[a][b][m][n] = (f32x4){0.f, 0.f, 0.f, 0.f};
;         cur = nxt; cA = nA; cB = nB; ++ui;
.LBB0_673:
	s_lshl_b64 s[4:5], s[26:27], 18
	s_add_u32 s30, s10, s4
	s_addc_u32 s31, s11, s5
	s_and_b64 s[4:5], s[8:9], exec
	s_cselect_b32 s25, s31, s37
	s_cselect_b32 s27, s30, s36
	s_add_u32 s8, s36, 0x20080
	s_addc_u32 s9, s37, 0
	s_add_u32 s36, s34, 0x100
	v_mov_b32_e32 v2, 0
	s_addc_u32 s37, s35, 0
	s_mov_b32 s44, -2
	v_mov_b32_e32 v3, v2
	v_mov_b64_e32 v[4:5], v[2:3]
	v_mov_b64_e32 v[6:7], v[2:3]
	v_mov_b64_e32 v[8:9], v[2:3]
	v_mov_b64_e32 v[10:11], v[2:3]
	v_mov_b64_e32 v[12:13], v[2:3]
	v_mov_b64_e32 v[14:15], v[2:3]
	v_mov_b64_e32 v[16:17], v[2:3]
	v_mov_b64_e32 v[26:27], v[2:3]
	v_mov_b64_e32 v[28:29], v[2:3]
	v_mov_b64_e32 v[30:31], v[2:3]
	v_mov_b64_e32 v[32:33], v[2:3]
	v_mov_b64_e32 v[42:43], v[2:3]
	v_mov_b64_e32 v[44:45], v[2:3]
	v_mov_b64_e32 v[46:47], v[2:3]
	v_mov_b64_e32 v[48:49], v[2:3]
	v_mov_b64_e32 v[18:19], v[2:3]
	v_mov_b64_e32 v[20:21], v[2:3]
	v_mov_b64_e32 v[22:23], v[2:3]
	v_mov_b64_e32 v[24:25], v[2:3]
	v_mov_b64_e32 v[34:35], v[2:3]
	v_mov_b64_e32 v[36:37], v[2:3]
	v_mov_b64_e32 v[38:39], v[2:3]
	v_mov_b64_e32 v[40:41], v[2:3]
	v_mov_b64_e32 v[50:51], v[2:3]
	v_mov_b64_e32 v[52:53], v[2:3]
	v_mov_b64_e32 v[54:55], v[2:3]
	v_mov_b64_e32 v[56:57], v[2:3]
	v_mov_b64_e32 v[58:59], v[2:3]
	v_mov_b64_e32 v[60:61], v[2:3]
	v_mov_b64_e32 v[62:63], v[2:3]
	v_mov_b64_e32 v[64:65], v[2:3]
	v_mov_b64_e32 v[66:67], v[2:3]
	v_mov_b64_e32 v[68:69], v[2:3]
	v_mov_b64_e32 v[70:71], v[2:3]
	v_mov_b64_e32 v[72:73], v[2:3]
	v_mov_b64_e32 v[74:75], v[2:3]
	v_mov_b64_e32 v[76:77], v[2:3]
	v_mov_b64_e32 v[78:79], v[2:3]
	v_mov_b64_e32 v[80:81], v[2:3]
	v_mov_b64_e32 v[90:91], v[2:3]
	v_mov_b64_e32 v[92:93], v[2:3]
	v_mov_b64_e32 v[94:95], v[2:3]
	v_mov_b64_e32 v[96:97], v[2:3]
	v_mov_b64_e32 v[106:107], v[2:3]
	v_mov_b64_e32 v[108:109], v[2:3]
	v_mov_b64_e32 v[110:111], v[2:3]
	v_mov_b64_e32 v[112:113], v[2:3]
	v_mov_b64_e32 v[82:83], v[2:3]
	v_mov_b64_e32 v[84:85], v[2:3]
	v_mov_b64_e32 v[86:87], v[2:3]
	v_mov_b64_e32 v[88:89], v[2:3]
	v_mov_b64_e32 v[98:99], v[2:3]
	v_mov_b64_e32 v[100:101], v[2:3]
	v_mov_b64_e32 v[102:103], v[2:3]
	v_mov_b64_e32 v[104:105], v[2:3]
	v_mov_b64_e32 v[114:115], v[2:3]
	v_mov_b64_e32 v[116:117], v[2:3]
	v_mov_b64_e32 v[118:119], v[2:3]
	v_mov_b64_e32 v[120:121], v[2:3]
	v_mov_b64_e32 v[122:123], v[2:3]
	v_mov_b64_e32 v[124:125], v[2:3]
	v_mov_b64_e32 v[126:127], v[2:3]
	v_mov_b64_e32 v[128:129], v[2:3]

; #define PG8_LDA(dst, b, h) do { _Pragma("unroll") for (int m = 0; m < 4; ++m) _Pragma("unroll") for (int k = 0; k < 2; ++k) dst[m][k] = *(const PG8_LAS bf16x8*)(lds + PG8_SA(b, h) + aoff + m * 2048 + k * 1024); } while (0)
; template <class Prob, class Epi, class Sched>
; __device__ __forceinline__ void gemm_phase(PG8_LAS unsigned char* lds, const Prob g, const Sched& S, const Epi& E) {
;     ...
;         const bool has_next = S.next(ui + 1, nxt);
;         const char* nA = has_next ? g.abase(nxt) : cA; const char* nB = has_next ? g.bbase(nxt) : cB;
;         for (int t = 0; t < nt; t += 2) {
;             const bool last = (t == nt - 2);
;             const char* a1 = cA + (size_t)(t + 1) * kstep;
;             const char* a2 = last ? nA : cA + (size_t)(t + 2) * kstep; const char* b2 = last ? nB : cB + (size_t)(t + 2) * kstep;
;             const char* a3 = a2 + kstep; const char* b3 = b2 + kstep;
;             PG8_LDB(B0, 0, 0); PG8_LDB(B1, 0, 1); PG8_SCHED; PG8_LDA(At, 0, 0); PG8_STAGE(PG8_SA(1, 1), a1 + hstepA, voffA);
;             PG8_WAIT_V(8); PG8_WAIT_L(0); PG8_BAR; PG8_MMA(0, 0, At, B0); PG8_MMA(0, 1, At, B1); PG8_BAR; PG8_SCHED;
;             PG8_LDA(At, 0, 1); PG8_STAGE(PG8_SB(0, 0), b2, voffB); PG8_STAGE(PG8_SB(0, 1), b2 + hstepB, voffB); PG8_STAGE(PG8_SA(0, 0), a2, voffA);
;             PG8_WAIT_V(8); PG8_WAIT_L(0); PG8_BAR; PG8_MMA(1, 0, At, B0); PG8_MMA(1, 1, At, B1); PG8_BAR; PG8_SCHED;
;             PG8_LDB(B0, 1, 0); PG8_LDB(B1, 1, 1); PG8_SCHED; PG8_LDA(At, 1, 0); PG8_STAGE(PG8_SA(0, 1), a2 + hstepA, voffA);
;             PG8_WAIT_V(8); PG8_WAIT_L(0); PG8_BAR; PG8_MMA(0, 0, At, B0); PG8_MMA(0, 1, At, B1); PG8_BAR; PG8_SCHED;
;             PG8_LDA(At, 1, 1); PG8_STAGE(PG8_SB(1, 0), b3, voffB); PG8_STAGE(PG8_SB(1, 1), b3 + hstepB, voffB); PG8_STAGE(PG8_SA(1, 0), a3, voffA);
;             PG8_WAIT_V(8); PG8_WAIT_L(0); PG8_BAR; PG8_MMA(1, 0, At, B0); PG8_MMA(1, 1, At, B1); PG8_BAR; PG8_SCHED;
;         }
;         if (wr == 0) PG8_BAR;
;         E(acc, cur, wr, wc, fr, fq);
;         if (!has_next) break;
; #pragma unroll
;         for (int a = 0; a < 2; ++a)
; #pragma unroll
;             for (int b = 0; b < 2; ++b)
; #pragma unroll
;                 for (int m = 0; m < 4; ++m)
; #pragma unroll
;                     for (int n = 0; n < 2; ++n) acc[a][b][m][n] = (f32x4){0.f, 0.f, 0.f, 0.f};
;         cur = nxt; cA = nA; cB = nB; ++ui;
.LBB0_693:
	s_ashr_i32 s21, s20, 31
	s_lshl_b64 s[4:5], s[20:21], 20
	s_add_u32 s22, s8, s4
	s_addc_u32 s23, s9, s5
	s_and_b64 s[4:5], s[6:7], exec
	s_cselect_b32 s21, s23, s27
	s_cselect_b32 s56, s22, s26
	s_ashr_i32 s19, s18, 31
	s_lshl_b64 s[4:5], s[18:19], 20
	s_add_u32 s24, s34, s4
	s_addc_u32 s25, s35, s5
	s_and_b64 s[4:5], s[6:7], exec
	s_cselect_b32 s19, s25, s29
	s_cselect_b32 s44, s24, s28
	s_add_u32 s26, s26, 0x80080
	s_addc_u32 s27, s27, 0
	s_add_u32 s45, s28, 0x100
	v_mov_b32_e32 v2, 0
	s_addc_u32 s57, s29, 0
	s_mov_b32 s58, -2
	v_mov_b32_e32 v3, v2
	v_mov_b64_e32 v[4:5], v[2:3]
	v_mov_b64_e32 v[6:7], v[2:3]
	v_mov_b64_e32 v[8:9], v[2:3]
	v_mov_b64_e32 v[14:15], v[2:3]
	v_mov_b64_e32 v[16:17], v[2:3]
	v_mov_b64_e32 v[22:23], v[2:3]
	v_mov_b64_e32 v[24:25], v[2:3]
	v_mov_b64_e32 v[30:31], v[2:3]
	v_mov_b64_e32 v[32:33], v[2:3]
	v_mov_b64_e32 v[38:39], v[2:3]
	v_mov_b64_e32 v[40:41], v[2:3]
	v_mov_b64_e32 v[46:47], v[2:3]
	v_mov_b64_e32 v[48:49], v[2:3]
	v_mov_b64_e32 v[54:55], v[2:3]
	v_mov_b64_e32 v[56:57], v[2:3]
	v_mov_b64_e32 v[10:11], v[2:3]
	v_mov_b64_e32 v[12:13], v[2:3]
	v_mov_b64_e32 v[18:19], v[2:3]
	v_mov_b64_e32 v[20:21], v[2:3]
	v_mov_b64_e32 v[26:27], v[2:3]
	v_mov_b64_e32 v[28:29], v[2:3]
	v_mov_b64_e32 v[34:35], v[2:3]
	v_mov_b64_e32 v[36:37], v[2:3]
	v_mov_b64_e32 v[42:43], v[2:3]
	v_mov_b64_e32 v[44:45], v[2:3]
	v_mov_b64_e32 v[50:51], v[2:3]
	v_mov_b64_e32 v[52:53], v[2:3]
	v_mov_b64_e32 v[58:59], v[2:3]
	v_mov_b64_e32 v[60:61], v[2:3]
	v_mov_b64_e32 v[62:63], v[2:3]
	v_mov_b64_e32 v[64:65], v[2:3]
	v_mov_b64_e32 v[66:67], v[2:3]
	v_mov_b64_e32 v[68:69], v[2:3]
	v_mov_b64_e32 v[70:71], v[2:3]
	v_mov_b64_e32 v[72:73], v[2:3]
	v_mov_b64_e32 v[78:79], v[2:3]
	v_mov_b64_e32 v[80:81], v[2:3]
	v_mov_b64_e32 v[86:87], v[2:3]
	v_mov_b64_e32 v[88:89], v[2:3]
	v_mov_b64_e32 v[94:95], v[2:3]
	v_mov_b64_e32 v[96:97], v[2:3]
	v_mov_b64_e32 v[102:103], v[2:3]
	v_mov_b64_e32 v[104:105], v[2:3]
	v_mov_b64_e32 v[114:115], v[2:3]
	v_mov_b64_e32 v[116:117], v[2:3]
	v_mov_b64_e32 v[118:119], v[2:3]
	v_mov_b64_e32 v[120:121], v[2:3]
	v_mov_b64_e32 v[74:75], v[2:3]
	v_mov_b64_e32 v[76:77], v[2:3]
	v_mov_b64_e32 v[82:83], v[2:3]
	v_mov_b64_e32 v[84:85], v[2:3]
	v_mov_b64_e32 v[90:91], v[2:3]
	v_mov_b64_e32 v[92:93], v[2:3]
	v_mov_b64_e32 v[98:99], v[2:3]
	v_mov_b64_e32 v[100:101], v[2:3]
	v_mov_b64_e32 v[106:107], v[2:3]
	v_mov_b64_e32 v[108:109], v[2:3]
	v_mov_b64_e32 v[110:111], v[2:3]
	v_mov_b64_e32 v[112:113], v[2:3]
	v_mov_b64_e32 v[122:123], v[2:3]
	v_mov_b64_e32 v[124:125], v[2:3]
	v_mov_b64_e32 v[126:127], v[2:3]
	v_mov_b64_e32 v[128:129], v[2:3]

; #define PG8_LDA(dst, b, h) do { _Pragma("unroll") for (int m = 0; m < 4; ++m) _Pragma("unroll") for (int k = 0; k < 2; ++k) dst[m][k] = *(const PG8_LAS bf16x8*)(lds + PG8_SA(b, h) + aoff + m * 2048 + k * 1024); } while (0)
; template <class Prob, class Epi, class Sched>
; __device__ __forceinline__ void gemm_phase(PG8_LAS unsigned char* lds, const Prob g, const Sched& S, const Epi& E) {
;     ...
;         const bool has_next = S.next(ui + 1, nxt);
;         const char* nA = has_next ? g.abase(nxt) : cA; const char* nB = has_next ? g.bbase(nxt) : cB;
;         for (int t = 0; t < nt; t += 2) {
;             const bool last = (t == nt - 2);
;             const char* a1 = cA + (size_t)(t + 1) * kstep;
;             const char* a2 = last ? nA : cA + (size_t)(t + 2) * kstep; const char* b2 = last ? nB : cB + (size_t)(t + 2) * kstep;
;             const char* a3 = a2 + kstep; const char* b3 = b2 + kstep;
;             PG8_LDB(B0, 0, 0); PG8_LDB(B1, 0, 1); PG8_SCHED; PG8_LDA(At, 0, 0); PG8_STAGE(PG8_SA(1, 1), a1 + hstepA, voffA);
;             PG8_WAIT_V(8); PG8_WAIT_L(0); PG8_BAR; PG8_MMA(0, 0, At, B0); PG8_MMA(0, 1, At, B1); PG8_BAR; PG8_SCHED;
;             PG8_LDA(At, 0, 1); PG8_STAGE(PG8_SB(0, 0), b2, voffB); PG8_STAGE(PG8_SB(0, 1), b2 + hstepB, voffB); PG8_STAGE(PG8_SA(0, 0), a2, voffA);
;             PG8_WAIT_V(8); PG8_WAIT_L(0); PG8_BAR; PG8_MMA(1, 0, At, B0); PG8_MMA(1, 1, At, B1); PG8_BAR; PG8_SCHED;
;             PG8_LDB(B0, 1, 0); PG8_LDB(B1, 1, 1); PG8_SCHED; PG8_LDA(At, 1, 0); PG8_STAGE(PG8_SA(0, 1), a2 + hstepA, voffA);
;             PG8_WAIT_V(8); PG8_WAIT_L(0); PG8_BAR; PG8_MMA(0, 0, At, B0); PG8_MMA(0, 1, At, B1); PG8_BAR; PG8_SCHED;
;             PG8_LDA(At, 1, 1); PG8_STAGE(PG8_SB(1, 0), b3, voffB); PG8_STAGE(PG8_SB(1, 1), b3 + hstepB, voffB); PG8_STAGE(PG8_SA(1, 0), a3, voffA);
;             PG8_WAIT_V(8); PG8_WAIT_L(0); PG8_BAR; PG8_MMA(1, 0, At, B0); PG8_MMA(1, 1, At, B1); PG8_BAR; PG8_SCHED;
;         }
;         if (wr == 0) PG8_BAR;
;         E(acc, cur, wr, wc, fr, fq);
;         if (!has_next) break;
; #pragma unroll
;         for (int a = 0; a < 2; ++a)
; #pragma unroll
;             for (int b = 0; b < 2; ++b)
; #pragma unroll
;                 for (int m = 0; m < 4; ++m)
; #pragma unroll
;                     for (int n = 0; n < 2; ++n) acc[a][b][m][n] = (f32x4){0.f, 0.f, 0.f, 0.f};
;         cur = nxt; cA = nA; cB = nB; ++ui;
.LBB0_757:
	s_ashr_i32 s21, s20, 31
	s_lshl_b64 s[4:5], s[20:21], 19
	s_add_u32 s22, s8, s4
	s_addc_u32 s23, s9, s5
	s_and_b64 s[4:5], s[6:7], exec
	s_cselect_b32 s21, s23, s27
	s_cselect_b32 s56, s22, s26
	s_ashr_i32 s19, s18, 31
	s_lshl_b64 s[4:5], s[18:19], 19
	s_add_u32 s24, s34, s4
	s_addc_u32 s25, s35, s5
	s_and_b64 s[4:5], s[6:7], exec
	s_cselect_b32 s19, s25, s29
	s_cselect_b32 s44, s24, s28
	s_add_u32 s26, s26, 0x40080
	s_addc_u32 s27, s27, 0
	s_add_u32 s45, s28, 0x100
	v_mov_b32_e32 v2, 0
	s_addc_u32 s57, s29, 0
	s_mov_b32 s58, -2
	v_mov_b32_e32 v3, v2
	v_mov_b64_e32 v[4:5], v[2:3]
	v_mov_b64_e32 v[6:7], v[2:3]
	v_mov_b64_e32 v[8:9], v[2:3]
	v_mov_b64_e32 v[18:19], v[2:3]
	v_mov_b64_e32 v[20:21], v[2:3]
	v_mov_b64_e32 v[22:23], v[2:3]
	v_mov_b64_e32 v[24:25], v[2:3]
	v_mov_b64_e32 v[34:35], v[2:3]
	v_mov_b64_e32 v[36:37], v[2:3]
	v_mov_b64_e32 v[38:39], v[2:3]
	v_mov_b64_e32 v[40:41], v[2:3]
	v_mov_b64_e32 v[50:51], v[2:3]
	v_mov_b64_e32 v[52:53], v[2:3]
	v_mov_b64_e32 v[54:55], v[2:3]
	v_mov_b64_e32 v[56:57], v[2:3]
	v_mov_b64_e32 v[10:11], v[2:3]
	v_mov_b64_e32 v[12:13], v[2:3]
	v_mov_b64_e32 v[14:15], v[2:3]
	v_mov_b64_e32 v[16:17], v[2:3]
	v_mov_b64_e32 v[26:27], v[2:3]
	v_mov_b64_e32 v[28:29], v[2:3]
	v_mov_b64_e32 v[30:31], v[2:3]
	v_mov_b64_e32 v[32:33], v[2:3]
	v_mov_b64_e32 v[42:43], v[2:3]
	v_mov_b64_e32 v[44:45], v[2:3]
	v_mov_b64_e32 v[46:47], v[2:3]
	v_mov_b64_e32 v[48:49], v[2:3]
	v_mov_b64_e32 v[58:59], v[2:3]
	v_mov_b64_e32 v[60:61], v[2:3]
	v_mov_b64_e32 v[62:63], v[2:3]
	v_mov_b64_e32 v[64:65], v[2:3]
	v_mov_b64_e32 v[66:67], v[2:3]
	v_mov_b64_e32 v[68:69], v[2:3]
	v_mov_b64_e32 v[70:71], v[2:3]
	v_mov_b64_e32 v[72:73], v[2:3]
	v_mov_b64_e32 v[82:83], v[2:3]
	v_mov_b64_e32 v[84:85], v[2:3]
	v_mov_b64_e32 v[86:87], v[2:3]
	v_mov_b64_e32 v[88:89], v[2:3]
	v_mov_b64_e32 v[98:99], v[2:3]
	v_mov_b64_e32 v[100:101], v[2:3]
	v_mov_b64_e32 v[102:103], v[2:3]
	v_mov_b64_e32 v[104:105], v[2:3]
	v_mov_b64_e32 v[114:115], v[2:3]
	v_mov_b64_e32 v[116:117], v[2:3]
	v_mov_b64_e32 v[118:119], v[2:3]
	v_mov_b64_e32 v[120:121], v[2:3]
	v_mov_b64_e32 v[74:75], v[2:3]
	v_mov_b64_e32 v[76:77], v[2:3]
	v_mov_b64_e32 v[78:79], v[2:3]
	v_mov_b64_e32 v[80:81], v[2:3]
	v_mov_b64_e32 v[90:91], v[2:3]
	v_mov_b64_e32 v[92:93], v[2:3]
	v_mov_b64_e32 v[94:95], v[2:3]
	v_mov_b64_e32 v[96:97], v[2:3]
	v_mov_b64_e32 v[106:107], v[2:3]
	v_mov_b64_e32 v[108:109], v[2:3]
	v_mov_b64_e32 v[110:111], v[2:3]
	v_mov_b64_e32 v[112:113], v[2:3]
	v_mov_b64_e32 v[122:123], v[2:3]
	v_mov_b64_e32 v[124:125], v[2:3]
	v_mov_b64_e32 v[126:127], v[2:3]
	v_mov_b64_e32 v[128:129], v[2:3]

; #define PG8_LDA(dst, b, h) do { _Pragma("unroll") for (int m = 0; m < 4; ++m) _Pragma("unroll") for (int k = 0; k < 2; ++k) dst[m][k] = *(const PG8_LAS bf16x8*)(lds + PG8_SA(b, h) + aoff + m * 2048 + k * 1024); } while (0)
; template <class Prob, class Epi, class Sched>
; __device__ __forceinline__ void gemm_phase(PG8_LAS unsigned char* lds, const Prob g, const Sched& S, const Epi& E) {
;     ...
;         const bool has_next = S.next(ui + 1, nxt);
;         const char* nA = has_next ? g.abase(nxt) : cA; const char* nB = has_next ? g.bbase(nxt) : cB;
;         for (int t = 0; t < nt; t += 2) {
;             const bool last = (t == nt - 2);
;             const char* a1 = cA + (size_t)(t + 1) * kstep;
;             const char* a2 = last ? nA : cA + (size_t)(t + 2) * kstep; const char* b2 = last ? nB : cB + (size_t)(t + 2) * kstep;
;             const char* a3 = a2 + kstep; const char* b3 = b2 + kstep;
;             PG8_LDB(B0, 0, 0); PG8_LDB(B1, 0, 1); PG8_SCHED; PG8_LDA(At, 0, 0); PG8_STAGE(PG8_SA(1, 1), a1 + hstepA, voffA);
;             PG8_WAIT_V(8); PG8_WAIT_L(0); PG8_BAR; PG8_MMA(0, 0, At, B0); PG8_MMA(0, 1, At, B1); PG8_BAR; PG8_SCHED;
;             PG8_LDA(At, 0, 1); PG8_STAGE(PG8_SB(0, 0), b2, voffB); PG8_STAGE(PG8_SB(0, 1), b2 + hstepB, voffB); PG8_STAGE(PG8_SA(0, 0), a2, voffA);
;             PG8_WAIT_V(8); PG8_WAIT_L(0); PG8_BAR; PG8_MMA(1, 0, At, B0); PG8_MMA(1, 1, At, B1); PG8_BAR; PG8_SCHED;
;             PG8_LDB(B0, 1, 0); PG8_LDB(B1, 1, 1); PG8_SCHED; PG8_LDA(At, 1, 0); PG8_STAGE(PG8_SA(0, 1), a2 + hstepA, voffA);
;             PG8_WAIT_V(8); PG8_WAIT_L(0); PG8_BAR; PG8_MMA(0, 0, At, B0); PG8_MMA(0, 1, At, B1); PG8_BAR; PG8_SCHED;
;             PG8_LDA(At, 1, 1); PG8_STAGE(PG8_SB(1, 0), b3, voffB); PG8_STAGE(PG8_SB(1, 1), b3 + hstepB, voffB); PG8_STAGE(PG8_SA(1, 0), a3, voffA);
;             PG8_WAIT_V(8); PG8_WAIT_L(0); PG8_BAR; PG8_MMA(1, 0, At, B0); PG8_MMA(1, 1, At, B1); PG8_BAR; PG8_SCHED;
;         }
;         if (wr == 0) PG8_BAR;
;         E(acc, cur, wr, wc, fr, fq);
;         if (!has_next) break;
; #pragma unroll
;         for (int a = 0; a < 2; ++a)
; #pragma unroll
;             for (int b = 0; b < 2; ++b)
; #pragma unroll
;                 for (int m = 0; m < 4; ++m)
; #pragma unroll
;                     for (int n = 0; n < 2; ++n) acc[a][b][m][n] = (f32x4){0.f, 0.f, 0.f, 0.f};
;         cur = nxt; cA = nA; cB = nB; ++ui;
.LBB0_822:
	s_ashr_i32 s37, s36, 31
	s_lshl_b64 s[4:5], s[36:37], 20
	s_add_u32 s52, s12, s4
	s_addc_u32 s53, s13, s5
	s_and_b64 s[4:5], s[10:11], exec
	s_cselect_b32 s37, s53, s57
	s_cselect_b32 s70, s52, s56
	s_ashr_i32 s35, s34, 31
	s_lshl_b64 s[4:5], s[34:35], 20
	s_add_u32 s54, s51, s4
	s_addc_u32 s55, s58, s5
	s_and_b64 s[4:5], s[10:11], exec
	s_cselect_b32 s35, s55, s69
	s_cselect_b32 s44, s54, s68
	s_add_u32 s56, s56, 0x80080
	s_addc_u32 s57, s57, 0
	s_add_u32 s45, s68, 0x100
	v_mov_b32_e32 v2, 0
	s_addc_u32 vcc_lo, s69, 0
	s_mov_b32 vcc_hi, -2
	v_mov_b32_e32 v3, v2
	v_mov_b64_e32 v[4:5], v[2:3]
	v_mov_b64_e32 v[6:7], v[2:3]
	v_mov_b64_e32 v[8:9], v[2:3]
	v_mov_b64_e32 v[18:19], v[2:3]
	v_mov_b64_e32 v[20:21], v[2:3]
	v_mov_b64_e32 v[22:23], v[2:3]
	v_mov_b64_e32 v[24:25], v[2:3]
	v_mov_b64_e32 v[50:51], v[2:3]
	v_mov_b64_e32 v[52:53], v[2:3]
	v_mov_b64_e32 v[54:55], v[2:3]
	v_mov_b64_e32 v[56:57], v[2:3]
	v_mov_b64_e32 v[82:83], v[2:3]
	v_mov_b64_e32 v[84:85], v[2:3]
	v_mov_b64_e32 v[86:87], v[2:3]
	v_mov_b64_e32 v[88:89], v[2:3]
	v_mov_b64_e32 v[10:11], v[2:3]
	v_mov_b64_e32 v[12:13], v[2:3]
	v_mov_b64_e32 v[14:15], v[2:3]
	v_mov_b64_e32 v[16:17], v[2:3]
	v_mov_b64_e32 v[26:27], v[2:3]
	v_mov_b64_e32 v[28:29], v[2:3]
	v_mov_b64_e32 v[30:31], v[2:3]
	v_mov_b64_e32 v[32:33], v[2:3]
	v_mov_b64_e32 v[74:75], v[2:3]
	v_mov_b64_e32 v[76:77], v[2:3]
	v_mov_b64_e32 v[78:79], v[2:3]
	v_mov_b64_e32 v[80:81], v[2:3]
	v_mov_b64_e32 v[90:91], v[2:3]
	v_mov_b64_e32 v[92:93], v[2:3]
	v_mov_b64_e32 v[94:95], v[2:3]
	v_mov_b64_e32 v[96:97], v[2:3]
	v_mov_b64_e32 v[98:99], v[2:3]
	v_mov_b64_e32 v[100:101], v[2:3]
	v_mov_b64_e32 v[102:103], v[2:3]
	v_mov_b64_e32 v[104:105], v[2:3]
	v_mov_b64_e32 v[114:115], v[2:3]
	v_mov_b64_e32 v[116:117], v[2:3]
	v_mov_b64_e32 v[118:119], v[2:3]
	v_mov_b64_e32 v[120:121], v[2:3]
	v_mov_b64_e32 v[130:131], v[2:3]
	v_mov_b64_e32 v[132:133], v[2:3]
	v_mov_b64_e32 v[134:135], v[2:3]
	v_mov_b64_e32 v[136:137], v[2:3]
	v_mov_b64_e32 v[146:147], v[2:3]
	v_mov_b64_e32 v[148:149], v[2:3]
	v_mov_b64_e32 v[150:151], v[2:3]
	v_mov_b64_e32 v[152:153], v[2:3]
	v_mov_b64_e32 v[106:107], v[2:3]
	v_mov_b64_e32 v[108:109], v[2:3]
	v_mov_b64_e32 v[110:111], v[2:3]
	v_mov_b64_e32 v[112:113], v[2:3]
	v_mov_b64_e32 v[122:123], v[2:3]
	v_mov_b64_e32 v[124:125], v[2:3]
	v_mov_b64_e32 v[126:127], v[2:3]
	v_mov_b64_e32 v[128:129], v[2:3]
	v_mov_b64_e32 v[138:139], v[2:3]
	v_mov_b64_e32 v[140:141], v[2:3]
	v_mov_b64_e32 v[142:143], v[2:3]
	v_mov_b64_e32 v[144:145], v[2:3]
	v_mov_b64_e32 v[154:155], v[2:3]
	v_mov_b64_e32 v[156:157], v[2:3]
	v_mov_b64_e32 v[158:159], v[2:3]
	v_mov_b64_e32 v[160:161], v[2:3]

; #define PG8_LDA(dst, b, h) do { _Pragma("unroll") for (int m = 0; m < 4; ++m) _Pragma("unroll") for (int k = 0; k < 2; ++k) dst[m][k] = *(const PG8_LAS bf16x8*)(lds + PG8_SA(b, h) + aoff + m * 2048 + k * 1024); } while (0)
; template <class Prob, class Epi, class Sched>
; __device__ __forceinline__ void gemm_phase(PG8_LAS unsigned char* lds, const Prob g, const Sched& S, const Epi& E) {
;     ...
;         const bool has_next = S.next(ui + 1, nxt);
;         const char* nA = has_next ? g.abase(nxt) : cA; const char* nB = has_next ? g.bbase(nxt) : cB;
;         for (int t = 0; t < nt; t += 2) {
;             const bool last = (t == nt - 2);
;             const char* a1 = cA + (size_t)(t + 1) * kstep;
;             const char* a2 = last ? nA : cA + (size_t)(t + 2) * kstep; const char* b2 = last ? nB : cB + (size_t)(t + 2) * kstep;
;             const char* a3 = a2 + kstep; const char* b3 = b2 + kstep;
;             PG8_LDB(B0, 0, 0); PG8_LDB(B1, 0, 1); PG8_SCHED; PG8_LDA(At, 0, 0); PG8_STAGE(PG8_SA(1, 1), a1 + hstepA, voffA);
;             PG8_WAIT_V(8); PG8_WAIT_L(0); PG8_BAR; PG8_MMA(0, 0, At, B0); PG8_MMA(0, 1, At, B1); PG8_BAR; PG8_SCHED;
;             PG8_LDA(At, 0, 1); PG8_STAGE(PG8_SB(0, 0), b2, voffB); PG8_STAGE(PG8_SB(0, 1), b2 + hstepB, voffB); PG8_STAGE(PG8_SA(0, 0), a2, voffA);
;             PG8_WAIT_V(8); PG8_WAIT_L(0); PG8_BAR; PG8_MMA(1, 0, At, B0); PG8_MMA(1, 1, At, B1); PG8_BAR; PG8_SCHED;
;             PG8_LDB(B0, 1, 0); PG8_LDB(B1, 1, 1); PG8_SCHED; PG8_LDA(At, 1, 0); PG8_STAGE(PG8_SA(0, 1), a2 + hstepA, voffA);
;             PG8_WAIT_V(8); PG8_WAIT_L(0); PG8_BAR; PG8_MMA(0, 0, At, B0); PG8_MMA(0, 1, At, B1); PG8_BAR; PG8_SCHED;
;             PG8_LDA(At, 1, 1); PG8_STAGE(PG8_SB(1, 0), b3, voffB); PG8_STAGE(PG8_SB(1, 1), b3 + hstepB, voffB); PG8_STAGE(PG8_SA(1, 0), a3, voffA);
;             PG8_WAIT_V(8); PG8_WAIT_L(0); PG8_BAR; PG8_MMA(1, 0, At, B0); PG8_MMA(1, 1, At, B1); PG8_BAR; PG8_SCHED;
;         }
;         if (wr == 0) PG8_BAR;
;         E(acc, cur, wr, wc, fr, fq);
;         if (!has_next) break;
; #pragma unroll
;         for (int a = 0; a < 2; ++a)
; #pragma unroll
;             for (int b = 0; b < 2; ++b)
; #pragma unroll
;                 for (int m = 0; m < 4; ++m)
; #pragma unroll
;                     for (int n = 0; n < 2; ++n) acc[a][b][m][n] = (f32x4){0.f, 0.f, 0.f, 0.f};
;         cur = nxt; cA = nA; cB = nB; ++ui;
.LBB0_866:
	s_ashr_i32 s37, s36, 31
	s_lshl_b64 s[4:5], s[36:37], 20
	s_add_u32 s42, s12, s4
	s_addc_u32 s43, s13, s5
	s_and_b64 s[4:5], s[10:11], exec
	s_cselect_b32 s37, s43, s55
	s_cselect_b32 s70, s42, s54
	s_ashr_i32 s35, s34, 31
	s_lshl_b64 s[4:5], s[34:35], 20
	s_add_u32 s52, s51, s4
	s_addc_u32 s53, s58, s5
	s_and_b64 s[4:5], s[10:11], exec
	s_cselect_b32 s35, s53, s57
	s_cselect_b32 s44, s52, s56
	s_add_u32 s54, s54, 0x80080
	s_addc_u32 s55, s55, 0
	s_add_u32 s45, s56, 0x100
	v_mov_b32_e32 v2, 0
	s_addc_u32 vcc_lo, s57, 0
	s_mov_b32 vcc_hi, -2
	v_mov_b32_e32 v3, v2
	v_mov_b64_e32 v[4:5], v[2:3]
	v_mov_b64_e32 v[6:7], v[2:3]
	v_mov_b64_e32 v[8:9], v[2:3]
	v_mov_b64_e32 v[18:19], v[2:3]
	v_mov_b64_e32 v[20:21], v[2:3]
	v_mov_b64_e32 v[22:23], v[2:3]
	v_mov_b64_e32 v[24:25], v[2:3]
	v_mov_b64_e32 v[34:35], v[2:3]
	v_mov_b64_e32 v[36:37], v[2:3]
	v_mov_b64_e32 v[38:39], v[2:3]
	v_mov_b64_e32 v[40:41], v[2:3]
	v_mov_b64_e32 v[50:51], v[2:3]
	v_mov_b64_e32 v[52:53], v[2:3]
	v_mov_b64_e32 v[54:55], v[2:3]
	v_mov_b64_e32 v[56:57], v[2:3]
	v_mov_b64_e32 v[10:11], v[2:3]
	v_mov_b64_e32 v[12:13], v[2:3]
	v_mov_b64_e32 v[14:15], v[2:3]
	v_mov_b64_e32 v[16:17], v[2:3]
	v_mov_b64_e32 v[26:27], v[2:3]
	v_mov_b64_e32 v[28:29], v[2:3]
	v_mov_b64_e32 v[30:31], v[2:3]
	v_mov_b64_e32 v[32:33], v[2:3]
	v_mov_b64_e32 v[42:43], v[2:3]
	v_mov_b64_e32 v[44:45], v[2:3]
	v_mov_b64_e32 v[46:47], v[2:3]
	v_mov_b64_e32 v[48:49], v[2:3]
	v_mov_b64_e32 v[58:59], v[2:3]
	v_mov_b64_e32 v[60:61], v[2:3]
	v_mov_b64_e32 v[62:63], v[2:3]
	v_mov_b64_e32 v[64:65], v[2:3]
	v_mov_b64_e32 v[98:99], v[2:3]
	v_mov_b64_e32 v[100:101], v[2:3]
	v_mov_b64_e32 v[102:103], v[2:3]
	v_mov_b64_e32 v[104:105], v[2:3]
	v_mov_b64_e32 v[114:115], v[2:3]
	v_mov_b64_e32 v[116:117], v[2:3]
	v_mov_b64_e32 v[118:119], v[2:3]
	v_mov_b64_e32 v[120:121], v[2:3]
	v_mov_b64_e32 v[130:131], v[2:3]
	v_mov_b64_e32 v[132:133], v[2:3]
	v_mov_b64_e32 v[134:135], v[2:3]
	v_mov_b64_e32 v[136:137], v[2:3]
	v_mov_b64_e32 v[146:147], v[2:3]
	v_mov_b64_e32 v[148:149], v[2:3]
	v_mov_b64_e32 v[150:151], v[2:3]
	v_mov_b64_e32 v[152:153], v[2:3]
	v_mov_b64_e32 v[106:107], v[2:3]
	v_mov_b64_e32 v[108:109], v[2:3]
	v_mov_b64_e32 v[110:111], v[2:3]
	v_mov_b64_e32 v[112:113], v[2:3]
	v_mov_b64_e32 v[122:123], v[2:3]
	v_mov_b64_e32 v[124:125], v[2:3]
	v_mov_b64_e32 v[126:127], v[2:3]
	v_mov_b64_e32 v[128:129], v[2:3]
	v_mov_b64_e32 v[138:139], v[2:3]
	v_mov_b64_e32 v[140:141], v[2:3]
	v_mov_b64_e32 v[142:143], v[2:3]
	v_mov_b64_e32 v[144:145], v[2:3]
	v_mov_b64_e32 v[154:155], v[2:3]
	v_mov_b64_e32 v[156:157], v[2:3]
	v_mov_b64_e32 v[158:159], v[2:3]
	v_mov_b64_e32 v[160:161], v[2:3]

; #define PG8_LDA(dst, b, h) do { _Pragma("unroll") for (int m = 0; m < 4; ++m) _Pragma("unroll") for (int k = 0; k < 2; ++k) dst[m][k] = *(const PG8_LAS bf16x8*)(lds + PG8_SA(b, h) + aoff + m * 2048 + k * 1024); } while (0)
; template <class Prob, class Epi, class Sched>
; __device__ __forceinline__ void gemm_phase(PG8_LAS unsigned char* lds, const Prob g, const Sched& S, const Epi& E) {
;     ...
;         const bool has_next = S.next(ui + 1, nxt);
;         const char* nA = has_next ? g.abase(nxt) : cA; const char* nB = has_next ? g.bbase(nxt) : cB;
;         for (int t = 0; t < nt; t += 2) {
;             const bool last = (t == nt - 2);
;             const char* a1 = cA + (size_t)(t + 1) * kstep;
;             const char* a2 = last ? nA : cA + (size_t)(t + 2) * kstep; const char* b2 = last ? nB : cB + (size_t)(t + 2) * kstep;
;             const char* a3 = a2 + kstep; const char* b3 = b2 + kstep;
;             PG8_LDB(B0, 0, 0); PG8_LDB(B1, 0, 1); PG8_SCHED; PG8_LDA(At, 0, 0); PG8_STAGE(PG8_SA(1, 1), a1 + hstepA, voffA);
;             PG8_WAIT_V(8); PG8_WAIT_L(0); PG8_BAR; PG8_MMA(0, 0, At, B0); PG8_MMA(0, 1, At, B1); PG8_BAR; PG8_SCHED;
;             PG8_LDA(At, 0, 1); PG8_STAGE(PG8_SB(0, 0), b2, voffB); PG8_STAGE(PG8_SB(0, 1), b2 + hstepB, voffB); PG8_STAGE(PG8_SA(0, 0), a2, voffA);
;             PG8_WAIT_V(8); PG8_WAIT_L(0); PG8_BAR; PG8_MMA(1, 0, At, B0); PG8_MMA(1, 1, At, B1); PG8_BAR; PG8_SCHED;
;             PG8_LDB(B0, 1, 0); PG8_LDB(B1, 1, 1); PG8_SCHED; PG8_LDA(At, 1, 0); PG8_STAGE(PG8_SA(0, 1), a2 + hstepA, voffA);
;             PG8_WAIT_V(8); PG8_WAIT_L(0); PG8_BAR; PG8_MMA(0, 0, At, B0); PG8_MMA(0, 1, At, B1); PG8_BAR; PG8_SCHED;
;             PG8_LDA(At, 1, 1); PG8_STAGE(PG8_SB(1, 0), b3, voffB); PG8_STAGE(PG8_SB(1, 1), b3 + hstepB, voffB); PG8_STAGE(PG8_SA(1, 0), a3, voffA);
;             PG8_WAIT_V(8); PG8_WAIT_L(0); PG8_BAR; PG8_MMA(1, 0, At, B0); PG8_MMA(1, 1, At, B1); PG8_BAR; PG8_SCHED;
;         }
;         if (wr == 0) PG8_BAR;
;         E(acc, cur, wr, wc, fr, fq);
;         if (!has_next) break;
; #pragma unroll
;         for (int a = 0; a < 2; ++a)
; #pragma unroll
;             for (int b = 0; b < 2; ++b)
; #pragma unroll
;                 for (int m = 0; m < 4; ++m)
; #pragma unroll
;                     for (int n = 0; n < 2; ++n) acc[a][b][m][n] = (f32x4){0.f, 0.f, 0.f, 0.f};
;         cur = nxt; cA = nA; cB = nB; ++ui;
.LBB0_952:
	s_ashr_i32 s25, s24, 31
	s_lshl_b64 s[4:5], s[24:25], 20
	s_add_u32 s26, s8, s4
	s_addc_u32 s27, s9, s5
	s_and_b64 s[4:5], s[6:7], exec
	s_cselect_b32 s25, s27, s31
	s_cselect_b32 s66, s26, s30
	s_ashr_i32 s23, s22, 31
	s_lshl_b64 s[4:5], s[22:23], 20
	s_add_u32 s28, s39, s4
	s_addc_u32 s29, s42, s5
	s_and_b64 s[4:5], s[6:7], exec
	s_cselect_b32 s23, s29, s35
	s_cselect_b32 s44, s28, s34
	s_add_u32 s30, s30, 0x80080
	s_addc_u32 s31, s31, 0
	s_add_u32 s45, s34, 0x100
	v_mov_b32_e32 v2, 0
	s_addc_u32 s68, s35, 0
	s_mov_b32 s69, -2
	v_mov_b32_e32 v3, v2
	v_mov_b64_e32 v[4:5], v[2:3]
	v_mov_b64_e32 v[10:11], v[2:3]
	v_mov_b64_e32 v[12:13], v[2:3]
	v_mov_b64_e32 v[18:19], v[2:3]
	v_mov_b64_e32 v[20:21], v[2:3]
	v_mov_b64_e32 v[26:27], v[2:3]
	v_mov_b64_e32 v[28:29], v[2:3]
	v_mov_b64_e32 v[34:35], v[2:3]
	v_mov_b64_e32 v[36:37], v[2:3]
	v_mov_b64_e32 v[42:43], v[2:3]
	v_mov_b64_e32 v[44:45], v[2:3]
	v_mov_b64_e32 v[50:51], v[2:3]
	v_mov_b64_e32 v[52:53], v[2:3]
	v_mov_b64_e32 v[74:75], v[2:3]
	v_mov_b64_e32 v[76:77], v[2:3]
	v_mov_b64_e32 v[6:7], v[2:3]
	v_mov_b64_e32 v[8:9], v[2:3]
	v_mov_b64_e32 v[14:15], v[2:3]
	v_mov_b64_e32 v[16:17], v[2:3]
	v_mov_b64_e32 v[22:23], v[2:3]
	v_mov_b64_e32 v[24:25], v[2:3]
	v_mov_b64_e32 v[30:31], v[2:3]
	v_mov_b64_e32 v[32:33], v[2:3]
	v_mov_b64_e32 v[38:39], v[2:3]
	v_mov_b64_e32 v[40:41], v[2:3]
	v_mov_b64_e32 v[46:47], v[2:3]
	v_mov_b64_e32 v[48:49], v[2:3]
	v_mov_b64_e32 v[58:59], v[2:3]
	v_mov_b64_e32 v[60:61], v[2:3]
	v_mov_b64_e32 v[86:87], v[2:3]
	v_mov_b64_e32 v[88:89], v[2:3]
	v_mov_b64_e32 v[98:99], v[2:3]
	v_mov_b64_e32 v[100:101], v[2:3]
	v_mov_b64_e32 v[106:107], v[2:3]
	v_mov_b64_e32 v[108:109], v[2:3]
	v_mov_b64_e32 v[114:115], v[2:3]
	v_mov_b64_e32 v[116:117], v[2:3]
	v_mov_b64_e32 v[122:123], v[2:3]
	v_mov_b64_e32 v[124:125], v[2:3]
	v_mov_b64_e32 v[130:131], v[2:3]
	v_mov_b64_e32 v[132:133], v[2:3]
	v_mov_b64_e32 v[138:139], v[2:3]
	v_mov_b64_e32 v[140:141], v[2:3]
	v_mov_b64_e32 v[146:147], v[2:3]
	v_mov_b64_e32 v[148:149], v[2:3]
	v_mov_b64_e32 v[154:155], v[2:3]
	v_mov_b64_e32 v[156:157], v[2:3]
	v_mov_b64_e32 v[102:103], v[2:3]
	v_mov_b64_e32 v[104:105], v[2:3]
	v_mov_b64_e32 v[110:111], v[2:3]
	v_mov_b64_e32 v[112:113], v[2:3]
	v_mov_b64_e32 v[118:119], v[2:3]
	v_mov_b64_e32 v[120:121], v[2:3]
	v_mov_b64_e32 v[126:127], v[2:3]
	v_mov_b64_e32 v[128:129], v[2:3]
	v_mov_b64_e32 v[134:135], v[2:3]
	v_mov_b64_e32 v[136:137], v[2:3]
	v_mov_b64_e32 v[142:143], v[2:3]
	v_mov_b64_e32 v[144:145], v[2:3]
	v_mov_b64_e32 v[150:151], v[2:3]
	v_mov_b64_e32 v[152:153], v[2:3]
	v_mov_b64_e32 v[158:159], v[2:3]
	v_mov_b64_e32 v[160:161], v[2:3]

; template <class Prob, class Epi, class Sched>
; __device__ __forceinline__ void gemm_phase(PG8_LAS unsigned char* lds, const Prob g, const Sched& S, const Epi& E) {
;     ...
;             const char* a2 = last ? nA : cA + (size_t)(t + 2) * kstep; const char* b2 = last ? nB : cB + (size_t)(t + 2) * kstep;
;             const char* a3 = a2 + kstep; const char* b3 = b2 + kstep;
;     ...
; #pragma unroll
;         for (int a = 0; a < 2; ++a)
; #pragma unroll
;             for (int b = 0; b < 2; ++b)
; #pragma unroll
;                 for (int m = 0; m < 4; ++m)
; #pragma unroll
;                     for (int n = 0; n < 2; ++n) acc[a][b][m][n] = (f32x4){0.f, 0.f, 0.f, 0.f};
;         cur = nxt; cA = nA; cB = nB; ++ui;
.LBB0_1020:
	s_add_u32 s44, s28, 0x100
	v_mov_b32_e32 v2, 0
	s_addc_u32 s45, s29, 0
	s_mov_b32 s64, -2
	v_mov_b32_e32 v3, v2
	v_mov_b64_e32 v[4:5], v[2:3]
	v_mov_b64_e32 v[6:7], v[2:3]
	v_mov_b64_e32 v[8:9], v[2:3]
	v_mov_b64_e32 v[18:19], v[2:3]
	v_mov_b64_e32 v[20:21], v[2:3]
	v_mov_b64_e32 v[22:23], v[2:3]
	v_mov_b64_e32 v[24:25], v[2:3]
	v_mov_b64_e32 v[34:35], v[2:3]
	v_mov_b64_e32 v[36:37], v[2:3]
	v_mov_b64_e32 v[38:39], v[2:3]
	v_mov_b64_e32 v[40:41], v[2:3]
	v_mov_b64_e32 v[50:51], v[2:3]
	v_mov_b64_e32 v[52:53], v[2:3]
	v_mov_b64_e32 v[54:55], v[2:3]
	v_mov_b64_e32 v[56:57], v[2:3]
	v_mov_b64_e32 v[10:11], v[2:3]
	v_mov_b64_e32 v[12:13], v[2:3]
	v_mov_b64_e32 v[14:15], v[2:3]
	v_mov_b64_e32 v[16:17], v[2:3]
	v_mov_b64_e32 v[26:27], v[2:3]
	v_mov_b64_e32 v[28:29], v[2:3]
	v_mov_b64_e32 v[30:31], v[2:3]
	v_mov_b64_e32 v[32:33], v[2:3]
	v_mov_b64_e32 v[42:43], v[2:3]
	v_mov_b64_e32 v[44:45], v[2:3]
	v_mov_b64_e32 v[46:47], v[2:3]
	v_mov_b64_e32 v[48:49], v[2:3]
	v_mov_b64_e32 v[58:59], v[2:3]
	v_mov_b64_e32 v[60:61], v[2:3]
	v_mov_b64_e32 v[62:63], v[2:3]
	v_mov_b64_e32 v[64:65], v[2:3]
	v_mov_b64_e32 v[66:67], v[2:3]
	v_mov_b64_e32 v[68:69], v[2:3]
	v_mov_b64_e32 v[70:71], v[2:3]
	v_mov_b64_e32 v[72:73], v[2:3]
	v_mov_b64_e32 v[82:83], v[2:3]
	v_mov_b64_e32 v[84:85], v[2:3]
	v_mov_b64_e32 v[86:87], v[2:3]
	v_mov_b64_e32 v[88:89], v[2:3]
	v_mov_b64_e32 v[98:99], v[2:3]
	v_mov_b64_e32 v[100:101], v[2:3]
	v_mov_b64_e32 v[102:103], v[2:3]
	v_mov_b64_e32 v[104:105], v[2:3]
	v_mov_b64_e32 v[122:123], v[2:3]
	v_mov_b64_e32 v[124:125], v[2:3]
	v_mov_b64_e32 v[134:135], v[2:3]
	v_mov_b64_e32 v[136:137], v[2:3]
	v_mov_b64_e32 v[74:75], v[2:3]
	v_mov_b64_e32 v[76:77], v[2:3]
	v_mov_b64_e32 v[78:79], v[2:3]
	v_mov_b64_e32 v[80:81], v[2:3]
	v_mov_b64_e32 v[90:91], v[2:3]
	v_mov_b64_e32 v[92:93], v[2:3]
	v_mov_b64_e32 v[94:95], v[2:3]
	v_mov_b64_e32 v[96:97], v[2:3]
	v_mov_b64_e32 v[106:107], v[2:3]
	v_mov_b64_e32 v[108:109], v[2:3]
	v_mov_b64_e32 v[110:111], v[2:3]
	v_mov_b64_e32 v[112:113], v[2:3]
	v_mov_b64_e32 v[154:155], v[2:3]
	v_mov_b64_e32 v[156:157], v[2:3]
	v_mov_b64_e32 v[158:159], v[2:3]
	v_mov_b64_e32 v[160:161], v[2:3]
